# attention phase: one static s_setprio 1 for waves 0-3 (older half) at phase entry, reset at phase exit; no other change vs v71
# baseline (speedup 1.0000x reference)
.LBB0_229:
	s_cmp_lt_i32 s88, 3
	s_cselect_b64 s[0:1], -1, 0
	s_and_b64 s[4:5], s[0:1], s[4:5]
	s_cmp_gt_i32 s92, 0
	s_cselect_b64 s[0:1], -1, 0
	s_and_b64 s[0:1], s[4:5], s[0:1]
	s_andn2_b64 vcc, exec, s[0:1]
	s_mov_b32 s28, 0
	s_cbranch_vccnz .LBB0_343
	v_writelane_b32 v253, s4, 48
	s_mov_b64 s[80:81], s[92:93]
	s_mov_b64 s[82:83], s[94:95]
	v_writelane_b32 v253, s5, 49
	s_mov_b64 s[76:77], s[88:89]
	v_writelane_b32 v253, s76, 50
	s_mul_i32 s60, s48, 0x600
	s_mul_hi_i32 s61, s48, 0x600
	v_writelane_b32 v253, s77, 51
	v_writelane_b32 v253, s78, 52
	v_writelane_b32 v253, s79, 53
	v_writelane_b32 v253, s80, 54
	v_writelane_b32 v253, s81, 55
	v_writelane_b32 v253, s82, 56
	v_writelane_b32 v253, s83, 57
	v_cvt_f32_u32_e32 v0, s96
	v_readlane_b32 s3, v253, 0
	s_cmp_ge_u32 s3, 0x100
	s_cbranch_scc1 .Latt_prio_set
	s_setprio 1
.Latt_prio_set:
	s_and_b32 s30, s3, 0xffffffc0
	s_lshl_b32 s0, s30, 2
	s_add_i32 s94, s0, 0
	v_readlane_b32 s4, v253, 4
	s_add_i32 s94, s94, 0x10000
	v_readlane_b32 s6, v253, 6
	v_readlane_b32 s7, v253, 7
	s_add_u32 s80, s6, 0x22b00000
	s_addc_u32 s81, s7, 0
	s_add_u32 s31, s6, 0x16900000
	s_addc_u32 s34, s7, 0
	s_add_i32 s0, s48, 1
	s_mul_hi_i32 s1, s0, 0x600
	s_add_i32 s0, s60, 0x600
	v_readlane_b32 s5, v253, 5
	v_writelane_b32 v253, s0, 58
	s_lshr_b32 s35, s3, 7
	s_ashr_i32 s97, s96, 31
	v_writelane_b32 v253, s1, 59
	v_rcp_iflag_f32_e32 v0, v0
	v_readlane_b32 s0, v253, 44
	s_lshl_b32 s62, s0, 11
	s_lshl_b32 s63, s0, 5
	s_lshl_b32 s0, s35, 11
	s_add_i32 s1, s0, 0
	s_and_b32 s64, s63, 32
	s_add_i32 s65, s1, 0x10800
	s_add_u32 s66, s6, 0x3db00000
	s_addc_u32 s67, s7, 0
	s_lshl_b32 s1, s64, 2
	s_sub_i32 s68, s65, s1
	s_or_b32 s1, s63, 8
	v_writelane_b32 v253, s1, 60
	s_or_b32 s1, s63, 9
	v_writelane_b32 v253, s1, 62
	s_or_b32 s1, s63, 10
	v_writelane_b32 v254, s1, 0
	s_or_b32 s1, s63, 11
	v_writelane_b32 v254, s1, 2
	s_or_b32 s1, s63, 16
	v_writelane_b32 v254, s1, 4
	s_or_b32 s1, s63, 17
	v_writelane_b32 v254, s1, 6
	s_or_b32 s1, s63, 18
	v_writelane_b32 v254, s1, 8
	s_or_b32 s1, s63, 19
	v_writelane_b32 v254, s1, 10
	s_or_b32 s1, s63, 24
	v_writelane_b32 v254, s1, 12
	s_or_b32 s1, s63, 25
	v_writelane_b32 v254, s1, 14
	s_or_b32 s1, s63, 26
	v_writelane_b32 v254, s1, 16
	s_or_b32 s1, s63, 27
	v_writelane_b32 v254, s1, 18
	s_lshl_b32 s1, s3, 1
	s_and_b32 s1, s1, 0x80
	s_sub_i32 s0, s0, s1
	s_add_i32 s0, s0, 0
	s_add_i32 s0, s0, 0x109fc
	v_writelane_b32 v254, s0, 20
	s_sub_i32 s0, 0, s1
	s_add_i32 s0, s0, 0x10d3c
	v_writelane_b32 v254, s0, 22
	s_add_i32 s0, 0, 0x18000
	v_writelane_b32 v254, s0, 24
	s_add_i32 s0, 0, 0x4000
	v_writelane_b32 v254, s0, 26
	v_writelane_b32 v254, s30, 28
	v_writelane_b32 v254, s31, 29
	v_writelane_b32 v254, s34, 31
	v_writelane_b32 v254, s35, 32
	v_writelane_b32 v254, s60, 34
	s_or_b32 s69, s63, 1
	v_mul_f32_e32 v0, 0x4f7ffffe, v0
	v_writelane_b32 v254, s61, 35
	v_writelane_b32 v254, s62, 36
	v_writelane_b32 v254, s63, 38
	v_writelane_b32 v254, s64, 40
	v_writelane_b32 v254, s65, 42
	v_writelane_b32 v254, s66, 44
	v_writelane_b32 v254, s67, 46
	v_writelane_b32 v254, s68, 48
	s_or_b32 s76, s63, 2
	v_cvt_u32_f32_e32 v142, v0
	v_writelane_b32 v254, s69, 50
	s_or_b32 s92, s63, 3
	v_writelane_b32 v254, s76, 52
	s_add_i32 s71, 0, 0x14000
	v_readlane_b32 s36, v253, 8
	v_writelane_b32 v254, s92, 54
	v_mov_b32_e32 v129, 0
	s_movk_i32 s70, 0xc0
	s_mov_b32 s85, 0x41300000
	s_movk_i32 s77, 0xffe0
	s_mov_b32 s33, 0xc3e00000
	v_mov_b32_e32 v143, 0xf149f2ca
	v_mov_b32_e32 v144, 0x43e00000
	v_mov_b32_e32 v145, 0x80
	v_mov_b32_e32 v146, 0x100
	v_mov_b32_e32 v147, 0x180
	v_mov_b32_e32 v148, 0x400
	v_mov_b32_e32 v149, 0x480
	v_mov_b32_e32 v150, 0x500
	v_mov_b32_e32 v151, 0x580
	v_mov_b32_e32 v152, 0x800
	v_mov_b32_e32 v153, 0x880
	v_mov_b32_e32 v154, 0x900
	v_mov_b32_e32 v155, 0x980
	v_mov_b32_e32 v156, 0xc00
	v_mov_b32_e32 v157, 0xc80
	v_mov_b32_e32 v158, 0xd00
	v_mov_b32_e32 v159, 0xd80
	s_mov_b32 s0, 0
	v_readlane_b32 s42, v253, 14
	v_readlane_b32 s43, v253, 15
	v_writelane_b32 v254, s71, 56
	v_readlane_b32 s37, v253, 9
	v_readlane_b32 s38, v253, 10
	v_readlane_b32 s39, v253, 11
	v_readlane_b32 s40, v253, 12
	v_readlane_b32 s41, v253, 13
	v_readlane_b32 s44, v253, 16
	v_readlane_b32 s45, v253, 17
	v_readlane_b32 s46, v253, 18
	v_readlane_b32 s47, v253, 19
	v_readlane_b32 s48, v253, 20
	v_readlane_b32 s49, v253, 21
	v_readlane_b32 s50, v253, 22
	v_readlane_b32 s51, v253, 23
	s_branch .LBB0_233

.LBB0_343:
	s_setprio 0
	s_cmp_gt_i32 s89, 3
	s_cselect_b64 s[0:1], -1, 0
	s_and_b64 s[4:5], s[4:5], s[0:1]
	s_andn2_b64 vcc, exec, s[4:5]
	s_cbranch_vccnz .LBB0_399
	s_waitcnt vmcnt(0)
	v_readlane_b32 s4, v253, 46
	v_readlane_b32 s5, v253, 47
	s_and_b64 vcc, exec, s[4:5]
	s_barrier
	s_cbranch_vccnz .LBB0_398
	v_mov_b32_e32 v0, 0
	s_nop 0
	v_mbcnt_lo_u32_b32 v0, -1, v0
	v_mbcnt_hi_u32_b32 v0, -1, v0
	v_cmp_eq_u32_e32 vcc, 0, v0
	s_and_saveexec_b64 s[4:5], vcc
	s_cbranch_execz .LBB0_397
	s_add_i32 s3, 0, 0x20160
	v_mov_b32_e32 v0, s3
	s_waitcnt vmcnt(0) expcnt(0) lgkmcnt(0)
	ds_read_b32 v2, v0
	s_add_i32 s3, 0, 0x20164
	v_mov_b32_e32 v0, s3
	ds_read_b32 v0, v0
	s_waitcnt lgkmcnt(1)
	v_cmp_ne_u32_e32 vcc, 0, v2
	s_cbranch_vccnz .LBB0_361
	v_readlane_b32 s6, v253, 2
	v_readlane_b32 s7, v253, 3
	v_readlane_b32 s40, v253, 4
	s_load_dwordx2 s[10:11], s[6:7], 0x4
	v_readlane_b32 s42, v253, 6
	v_readlane_b32 s43, v253, 7
	s_add_u32 s6, s42, 0x4200
	s_addc_u32 s7, s43, 0
	s_add_u32 s8, s42, 0x4400
	s_addc_u32 s9, s43, 0
	s_waitcnt lgkmcnt(0)
	s_mul_i32 s3, s10, s96
	s_add_u32 s10, s42, 0x4500
	s_mul_i32 s3, s3, s11
	s_addc_u32 s11, s43, 0
	s_add_u32 s12, s42, 0x4600
	s_addc_u32 s13, s43, 0
	s_add_u32 s14, s42, 0x4700
	s_addc_u32 s15, s43, 0
	s_add_u32 s16, s42, 0x4800
	s_addc_u32 s17, s43, 0
	s_add_u32 s18, s42, 0x4900
	s_addc_u32 s19, s43, 0
	s_add_u32 s20, s42, 0x4a00
	s_addc_u32 s21, s43, 0
	s_add_u32 s22, s42, 0x4b00
	s_addc_u32 s23, s43, 0
	s_add_u32 s24, s42, 0x4c00
	s_addc_u32 s25, s43, 0
	s_add_u32 s26, s42, 0x4d00
	s_addc_u32 s27, s43, 0
	s_add_u32 s28, s42, 0x4e00
	s_addc_u32 s29, s43, 0
	s_add_u32 s30, s42, 0x4f00
	s_addc_u32 s31, s43, 0
	s_add_u32 s34, s42, 0x5000
	s_addc_u32 s35, s43, 0
	s_add_u32 s36, s42, 0x5100
	s_addc_u32 s37, s43, 0
	s_add_u32 s38, s42, 0x5200
	s_addc_u32 s39, s43, 0
	v_readlane_b32 s41, v253, 5
	s_add_u32 s40, s42, 0x5300
	s_addc_u32 s41, s43, 0
	s_mov_b32 s33, 1
	v_mov_b32_e32 v16, 0
	s_branch .LBB0_349
